# gather: epilogue row loads issued at the top of the token's last expert group, epilogue is fma+stores only
# speedup vs baseline: 1.0090x; 1.0090x over previous
.LBB0_1060:
	v_ashrrev_i32_e32 v4, 11, v132
	v_mul_i32_i24_e32 v4, 0x1800, v4
	v_readlane_b32 s76, v248, 40
	v_ashrrev_i32_e32 v5, 31, v4
	v_readlane_b32 s90, v248, 54
	v_readlane_b32 s91, v248, 55
	v_lshl_add_u64 v[18:19], v[8:9], 2, v[2:3]
	v_add_u32_e32 v132, s62, v132
	v_lshl_add_u64 v[4:5], v[4:5], 2, s[90:91]
	v_lshl_add_u64 v[16:17], v[4:5], 0, v[76:77]
	v_add_co_u32_e32 v20, vcc, s35, v16
	v_readlane_b32 s77, v248, 41
	s_nop 0
	v_addc_co_u32_e32 v21, vcc, 0, v17, vcc
	v_min_i32_e32 v176, 0x7fff, v132
	v_ashrrev_i32_e32 v177, 31, v176
	v_lshlrev_b64 v[178:179], 9, v[176:177]
	v_lshl_or_b32 v178, v128, 2, v178
	v_lshl_add_u64 v[180:181], s[74:75], 0, v[178:179]
	global_load_dword v160, v[180:181], off
	global_load_dword v162, v[180:181], off offset:256
	v_lshlrev_b64 v[180:181], 11, v[176:177]
	v_lshl_add_u64 v[180:181], v[0:1], 0, v[180:181]
	global_load_dwordx4 v[164:167], v[180:181], off
	global_load_dwordx4 v[168:171], v[180:181], off offset:16
	v_lshl_add_u64 v[180:181], s[16:17], 0, v[178:179]
	v_or_b32_e32 v178, 0x100, v178
	v_lshl_add_u64 v[178:179], s[16:17], 0, v[178:179]
	global_load_dword v172, v[180:181], off
	global_load_dword v173, v[178:179], off
	v_lshl_add_u64 v[16:17], v[16:17], 0, s[20:21]
	v_cmp_lt_i32_e32 vcc, s36, v132
	s_or_b64 s[18:19], vcc, s[18:19]
	v_readlane_b32 s78, v248, 42
	v_readlane_b32 s79, v248, 43
	v_readlane_b32 s80, v248, 44
	v_readlane_b32 s81, v248, 45
	v_readlane_b32 s82, v248, 46
	v_readlane_b32 s83, v248, 47
	v_readlane_b32 s84, v248, 48
	v_readlane_b32 s85, v248, 49
	v_readlane_b32 s86, v248, 50
	v_readlane_b32 s87, v248, 51
	v_readlane_b32 s88, v248, 52
	v_readlane_b32 s89, v248, 53
	s_waitcnt vmcnt(0)
	v_pk_fma_f32 v[4:5], v[38:39], v[184:185], v[188:189]
	v_pk_fma_f32 v[6:7], v[40:41], v[186:187], v[190:191]
	global_store_dwordx4 v[18:19], v[4:7], off
	v_ashrrev_i32_e32 v161, 31, v160
	v_ashrrev_i32_e32 v163, 31, v162
	v_lshlrev_b64 v[176:177], 2, v[160:161]
	v_lshlrev_b64 v[178:179], 2, v[162:163]
	v_lshl_add_u64 v[180:181], s[54:55], 0, v[176:177]
	v_lshl_add_u64 v[176:177], s[56:57], 0, v[176:177]
	v_lshl_add_u64 v[182:183], s[54:55], 0, v[178:179]
	v_lshl_add_u64 v[178:179], s[56:57], 0, v[178:179]
	global_load_dword v174, v[176:177], off
	global_load_dword v175, v[178:179], off
	global_load_dword v161, v[180:181], off
	global_load_dword v163, v[182:183], off
	v_pk_fma_f32 v[8:9], v[34:35], v[192:193], v[196:197]
	v_pk_fma_f32 v[10:11], v[36:37], v[194:195], v[198:199]
	global_store_dwordx4 v[18:19], v[8:11], off offset:16
	v_pk_fma_f32 v[12:13], v[28:29], v[200:201], v[204:205]
	v_pk_fma_f32 v[14:15], v[30:31], v[202:203], v[206:207]
	global_store_dwordx4 v[18:19], v[12:15], off offset:32
	v_pk_fma_f32 v[216:217], v[26:27], v[208:209], v[212:213]
	v_pk_fma_f32 v[218:219], v[32:33], v[210:211], v[214:215]
	global_store_dwordx4 v[18:19], v[216:219], off offset:48
	s_waitcnt vmcnt(3)
	s_andn2_b64 exec, exec, s[18:19]
	s_cbranch_execz .LBB0_1067
.LBB0_1061:
	v_ashrrev_i32_e32 v133, 31, v132
	v_mov_b32_e32 v4, v160
	v_mov_b32_e32 v5, v161
	v_mov_b32_e32 v6, v162
	v_mov_b32_e32 v7, v163
	s_mov_b32 s22, 0
	v_mov_b32_e32 v38, 0
	v_mov_b32_e32 v39, v77
	v_mov_b32_e32 v40, 0
	v_mov_b32_e32 v41, v77
	v_mov_b32_e32 v34, 0
	v_mov_b32_e32 v35, v77
	v_mov_b32_e32 v36, 0
	v_mov_b32_e32 v37, v77
	v_mov_b32_e32 v28, 0
	v_mov_b32_e32 v29, v77
	v_mov_b32_e32 v30, 0
	v_mov_b32_e32 v31, v77
	v_mov_b32_e32 v26, 0
	v_mov_b32_e32 v27, v77
	v_mov_b32_e32 v32, 0
	v_lshlrev_b64 v[8:9], 10, v[132:133]
	v_lshlrev_b32_e32 v10, 16, v164
	v_and_b32_e32 v11, 0xffff0000, v164
	v_lshlrev_b32_e32 v12, 16, v165
	v_and_b32_e32 v13, 0xffff0000, v165
	v_lshlrev_b32_e32 v14, 16, v166
	v_and_b32_e32 v15, 0xffff0000, v166
	v_lshlrev_b32_e32 v16, 16, v167
	v_and_b32_e32 v17, 0xffff0000, v167
	v_lshlrev_b32_e32 v18, 16, v168
	v_and_b32_e32 v19, 0xffff0000, v168
	v_lshlrev_b32_e32 v20, 16, v169
	v_and_b32_e32 v21, 0xffff0000, v169
	v_lshlrev_b32_e32 v22, 16, v170
	v_and_b32_e32 v23, 0xffff0000, v170
	v_lshlrev_b32_e32 v24, 16, v171
	v_and_b32_e32 v25, 0xffff0000, v171
	v_mul_f32_e32 v87, v172, v174
	v_mul_f32_e32 v88, v173, v175
	v_mov_b32_e32 v33, v77
	v_lshl_add_u64 v[220:221], v[8:9], 2, v[2:3]
	v_ashrrev_i32_e32 v224, 11, v132
	v_mul_i32_i24_e32 v224, 0x1800, v224
	v_readlane_b32 s90, v248, 54
	v_ashrrev_i32_e32 v225, 31, v224
	v_readlane_b32 s91, v248, 55
	s_nop 3
	v_lshl_add_u64 v[224:225], v[224:225], 2, s[90:91]
	v_lshl_add_u64 v[224:225], v[224:225], 0, v[76:77]
	v_lshl_add_u64 v[222:223], v[224:225], 0, s[20:21]
	s_branch .LBB0_1063

.LBB0_1063:
	s_cmpk_lg_u32 s22, 0x70
	s_cbranch_scc1 .Lg_noepf
	global_load_dwordx4 v[184:187], v[222:223], off
	global_load_dwordx4 v[188:191], v[220:221], off
	global_load_dwordx4 v[192:195], v[222:223], off offset:16
	global_load_dwordx4 v[196:199], v[220:221], off offset:16
	global_load_dwordx4 v[200:203], v[222:223], off offset:32
	global_load_dwordx4 v[204:207], v[220:221], off offset:32
	global_load_dwordx4 v[208:211], v[222:223], off offset:48
	global_load_dwordx4 v[212:215], v[220:221], off offset:48
